# v32 plus finalize weight-load prefetch, saddr-form K-loop LDS-DMA and out-proj EpiResid counted stats waits stacked
# baseline (speedup 1.0000x reference)
.LBB0_967:
	v_lshl_add_u32 v224, s28, 8, v250
	v_ashrrev_i32_e32 v225, 31, v224
	v_mov_b32_e32 v234, 0x45000000
	v_mov_b32_e32 v237, 0x45000000
	v_mov_b32_e32 v236, 0
	s_and_b64 vcc, exec, s[10:11]
	v_mov_b32_e32 v240, 0
	v_mov_b32_e32 v238, 0x45000000
	v_mov_b32_e32 v241, 0x45000000
	s_cbranch_vccnz .LBB0_969
	v_lshl_add_u64 v[162:163], v[224:225], 3, s[20:21]
	global_load_dwordx2 v[240:241], v[162:163], off

.LBB0_971:
	v_lshlrev_b64 v[162:163], 13, v[230:231]
	v_lshl_add_u64 v[162:163], s[4:5], 0, v[162:163]
	v_lshl_add_u64 v[162:163], v[222:223], 2, v[162:163]
	global_load_dwordx4 v[190:193], v[162:163], off
	global_load_dwordx4 v[186:189], v[162:163], off offset:64
	global_load_dwordx4 v[182:185], v[162:163], off offset:512
	global_load_dwordx4 v[178:181], v[162:163], off offset:576
	v_or_b32_e32 v226, 32, v224
	s_and_b64 vcc, exec, s[10:11]
	v_ashrrev_i32_e32 v227, 31, v226
	s_cbranch_vccnz .LBB0_973
	v_lshl_add_u64 v[162:163], v[226:227], 3, s[20:21]
	global_load_dwordx2 v[232:233], v[162:163], off
	s_branch .LBB0_974
.LBB0_973:
	v_mov_b32_e32 v233, 0x45000000
	v_mov_b32_e32 v232, 0
.LBB0_974:
	v_lshlrev_b64 v[162:163], 13, v[226:227]
	v_lshl_add_u64 v[162:163], s[4:5], 0, v[162:163]
	v_lshl_add_u64 v[162:163], v[222:223], 2, v[162:163]
	global_load_dwordx4 v[174:177], v[162:163], off
	global_load_dwordx4 v[170:173], v[162:163], off offset:64
	global_load_dwordx4 v[166:169], v[162:163], off offset:512
	s_nop 0
	global_load_dwordx4 v[162:165], v[162:163], off offset:576
	s_mov_b32 s2, 0x3a000000
	s_nop 0
	s_waitcnt vmcnt(0)
	v_mov_b32_e32 v238, v241
	v_mul_f32_e32 v212, s2, v240
	v_cndmask_b32_e64 v239, v212, 0, s[58:59]
	v_mov_b32_e32 v212, s2
	v_mov_b32_e32 v213, v239
	v_pk_mul_f32 v[212:213], v[238:239], v[212:213]
	s_waitcnt vmcnt(0)
	v_sub_f32_e32 v207, v207, v239
	v_sub_f32_e32 v212, v212, v213
	v_add_f32_e32 v212, 0x3727c5ac, v212
	v_rsq_f32_e32 v214, v212
	v_sub_f32_e32 v206, v206, v239
	v_sub_f32_e32 v209, v209, v239
	v_sub_f32_e32 v208, v208, v239
	v_cndmask_b32_e64 v214, v214, 1.0, s[58:59]
	v_lshlrev_b64 v[212:213], 11, v[224:225]
	v_pk_mul_f32 v[208:209], v[208:209], v[214:215] op_sel_hi:[1,0]
	v_pk_mul_f32 v[206:207], v[206:207], v[214:215] op_sel_hi:[1,0]
	v_lshl_add_u64 v[212:213], v[212:213], 0, v[222:223]
	v_pk_fma_f32 v[206:207], v[90:91], v[206:207], v[94:95]
	v_pk_fma_f32 v[208:209], v[92:93], v[208:209], v[96:97]
	v_pk_fma_f32 v[158:159], v[206:207], s[76:77], v[158:159] op_sel_hi:[1,0,1]
	v_pk_fma_f32 v[160:161], v[208:209], s[76:77], v[160:161] op_sel_hi:[1,0,1]
	v_lshl_add_u64 v[206:207], v[212:213], 2, s[12:13]
	v_cvt_pk_bf16_f32 v208, v158, v159
	v_lshl_add_u64 v[212:213], v[212:213], 1, s[14:15]
	global_store_dwordx4 v[206:207], v[158:161], off
	v_cvt_pk_bf16_f32 v209, v160, v161
	global_store_dwordx2 v[212:213], v[208:209], off
	v_add_f32_e32 v208, v158, v159
	v_mul_f32_e32 v159, v159, v159
	v_fmac_f32_e32 v159, v158, v158
	v_mul_f32_e32 v158, v161, v161
	v_add_f32_e32 v209, v160, v161
	v_fmac_f32_e32 v158, v160, v160
	v_add_f32_e32 v208, v208, v209
	v_add_f32_e32 v209, v159, v158
	v_sub_f32_e32 v159, v203, v239
	v_sub_f32_e32 v158, v202, v239
	v_sub_f32_e32 v161, v205, v239
	v_sub_f32_e32 v160, v204, v239
	v_pk_mul_f32 v[160:161], v[160:161], v[214:215] op_sel_hi:[1,0]
	v_pk_mul_f32 v[158:159], v[158:159], v[214:215] op_sel_hi:[1,0]
	v_pk_fma_f32 v[160:161], v[76:77], v[160:161], v[80:81]
	v_pk_fma_f32 v[158:159], v[74:75], v[158:159], v[78:79]
	v_pk_fma_f32 v[156:157], v[160:161], s[76:77], v[156:157] op_sel_hi:[1,0,1]
	v_pk_fma_f32 v[154:155], v[158:159], s[76:77], v[154:155] op_sel_hi:[1,0,1]
	global_store_dwordx4 v[206:207], v[154:157], off offset:64
	v_cvt_pk_bf16_f32 v158, v154, v155
	v_cvt_pk_bf16_f32 v159, v156, v157
	global_store_dwordx2 v[212:213], v[158:159], off offset:32
	v_add_f32_e32 v158, v154, v155
	v_mul_f32_e32 v155, v155, v155
	v_fmac_f32_e32 v155, v154, v154
	v_mul_f32_e32 v154, v157, v157
	v_fmac_f32_e32 v154, v156, v156
	v_add_f32_e32 v159, v156, v157
	v_add_f32_e32 v154, v155, v154
	v_add_f32_e32 v158, v158, v159
	v_add_f32_e32 v159, v209, v154
	v_sub_f32_e32 v155, v199, v239
	v_sub_f32_e32 v154, v198, v239
	v_sub_f32_e32 v157, v201, v239
	v_sub_f32_e32 v156, v200, v239
	v_pk_mul_f32 v[156:157], v[156:157], v[214:215] op_sel_hi:[1,0]
	v_pk_mul_f32 v[154:155], v[154:155], v[214:215] op_sel_hi:[1,0]
	v_pk_fma_f32 v[156:157], v[84:85], v[156:157], v[88:89]
	v_pk_fma_f32 v[154:155], v[82:83], v[154:155], v[86:87]
	v_pk_fma_f32 v[152:153], v[156:157], s[76:77], v[152:153] op_sel_hi:[1,0,1]
	v_pk_fma_f32 v[150:151], v[154:155], s[76:77], v[150:151] op_sel_hi:[1,0,1]
	global_store_dwordx4 v[206:207], v[150:153], off offset:512
	v_cvt_pk_bf16_f32 v154, v150, v151
	v_cvt_pk_bf16_f32 v155, v152, v153
	global_store_dwordx2 v[212:213], v[154:155], off offset:256
	v_add_f32_e32 v154, v150, v151
	v_mul_f32_e32 v151, v151, v151
	v_fmac_f32_e32 v151, v150, v150
	v_mul_f32_e32 v150, v153, v153
	v_fmac_f32_e32 v150, v152, v152
	v_add_f32_e32 v155, v152, v153
	v_add_f32_e32 v150, v151, v150
	v_add_f32_e32 v154, v154, v155
	v_add_f32_e32 v155, v150, v159
	v_sub_f32_e32 v151, v195, v239
	v_sub_f32_e32 v150, v194, v239
	v_sub_f32_e32 v153, v197, v239
	v_sub_f32_e32 v152, v196, v239
	v_pk_mul_f32 v[152:153], v[152:153], v[214:215] op_sel_hi:[1,0]
	v_pk_mul_f32 v[150:151], v[150:151], v[214:215] op_sel_hi:[1,0]
	v_pk_fma_f32 v[152:153], v[68:69], v[152:153], v[72:73]
	v_pk_fma_f32 v[150:151], v[66:67], v[150:151], v[70:71]
	v_pk_fma_f32 v[148:149], v[152:153], s[76:77], v[148:149] op_sel_hi:[1,0,1]
	v_pk_fma_f32 v[146:147], v[150:151], s[76:77], v[146:147] op_sel_hi:[1,0,1]
	global_store_dwordx4 v[206:207], v[146:149], off offset:576
	v_cvt_pk_bf16_f32 v150, v146, v147
	v_cvt_pk_bf16_f32 v151, v148, v149
	global_store_dwordx2 v[212:213], v[150:151], off offset:288
	v_add_f32_e32 v150, v146, v147
	v_mul_f32_e32 v147, v147, v147
	v_add_f32_e32 v208, 0, v208
	v_fmac_f32_e32 v147, v146, v146
	v_mul_f32_e32 v146, v149, v149
	v_add_f32_e32 v158, v158, v208
	v_add_f32_e32 v151, v148, v149
	v_fmac_f32_e32 v146, v148, v148
	v_add_f32_e32 v154, v154, v158
	v_add_f32_e32 v150, v150, v151
	v_add_f32_e32 v146, v147, v146
	v_add_f32_e32 v150, v150, v154
	v_add_f32_e32 v148, v146, v155
	v_mov_b32_e32 v146, v150
	v_mov_b32_e32 v149, v148
	s_nop 0
	v_permlane16_swap_b32_e32 v150, v146
	v_permlane16_swap_b32_e32 v148, v149
	v_add_f32_e32 v146, v150, v146
	v_add_f32_e32 v148, v148, v149
	v_mov_b32_e32 v147, v146
	v_mov_b32_e32 v149, v148
	s_nop 0
	v_permlane32_swap_b32_e32 v146, v147
	v_permlane32_swap_b32_e32 v148, v149
	s_and_saveexec_b64 s[2:3], s[6:7]
	s_cbranch_execz .LBB0_976
	v_add_f32_e32 v148, v148, v149
	v_add_f32_e32 v149, v146, v147
	v_lshl_add_u64 v[146:147], v[224:225], 3, s[18:19]
	global_atomic_add_f32 v[146:147], v149, off
	global_atomic_add_f32 v[146:147], v148, off offset:4
.LBB0_976:
	s_or_b64 exec, exec, s[2:3]
	v_or_b32_e32 v194, 48, v224
	s_and_b64 vcc, exec, s[10:11]
	v_ashrrev_i32_e32 v195, 31, v194
	s_cbranch_vccnz .LBB0_978
	v_lshl_add_u64 v[146:147], v[194:195], 3, s[20:21]
	global_load_dwordx2 v[198:199], v[146:147], off
	s_branch .LBB0_979
.LBB0_978:
	v_mov_b32_e32 v199, 0x45000000
	v_mov_b32_e32 v198, 0
.LBB0_979:
	v_lshlrev_b64 v[146:147], 13, v[194:195]
	v_lshl_add_u64 v[146:147], s[4:5], 0, v[146:147]
	v_lshl_add_u64 v[146:147], v[222:223], 2, v[146:147]
	global_load_dwordx4 v[158:161], v[146:147], off
	global_load_dwordx4 v[154:157], v[146:147], off offset:64
	global_load_dwordx4 v[150:153], v[146:147], off offset:512
	s_nop 0
	global_load_dwordx4 v[146:149], v[146:147], off offset:576
	s_mov_b32 s2, 0x3a000000
	s_nop 0
	v_mov_b32_e32 v234, v237
	v_mul_f32_e32 v197, s2, v236
	v_cndmask_b32_e64 v235, v197, 0, s[58:59]
	v_mov_b32_e32 v200, s2
	v_mov_b32_e32 v201, v235
	v_pk_mul_f32 v[200:201], v[234:235], v[200:201]
	v_sub_f32_e32 v191, v191, v235
	v_sub_f32_e32 v197, v200, v201
	v_add_f32_e32 v197, 0x3727c5ac, v197
	v_rsq_f32_e32 v197, v197
	v_sub_f32_e32 v190, v190, v235
	v_sub_f32_e32 v193, v193, v235
	v_sub_f32_e32 v192, v192, v235
	v_cndmask_b32_e64 v202, v197, 1.0, s[58:59]
	v_lshlrev_b64 v[200:201], 11, v[230:231]
	v_pk_mul_f32 v[192:193], v[192:193], v[202:203] op_sel_hi:[1,0]
	v_pk_mul_f32 v[190:191], v[190:191], v[202:203] op_sel_hi:[1,0]
	v_lshl_add_u64 v[200:201], v[200:201], 0, v[222:223]
	v_pk_fma_f32 v[190:191], v[90:91], v[190:191], v[94:95]
	v_pk_fma_f32 v[192:193], v[92:93], v[192:193], v[96:97]
	v_pk_fma_f32 v[142:143], v[190:191], s[76:77], v[142:143] op_sel_hi:[1,0,1]
	v_pk_fma_f32 v[144:145], v[192:193], s[76:77], v[144:145] op_sel_hi:[1,0,1]
	v_lshl_add_u64 v[190:191], v[200:201], 2, s[12:13]
	v_cvt_pk_bf16_f32 v192, v142, v143
	v_lshl_add_u64 v[200:201], v[200:201], 1, s[14:15]
	global_store_dwordx4 v[190:191], v[142:145], off
	v_cvt_pk_bf16_f32 v193, v144, v145
	global_store_dwordx2 v[200:201], v[192:193], off
	v_add_f32_e32 v192, v142, v143
	v_mul_f32_e32 v143, v143, v143
	v_fmac_f32_e32 v143, v142, v142
	v_mul_f32_e32 v142, v145, v145
	v_add_f32_e32 v193, v144, v145
	v_fmac_f32_e32 v142, v144, v144
	v_add_f32_e32 v192, v192, v193
	v_add_f32_e32 v193, v143, v142
	v_sub_f32_e32 v143, v187, v235
	v_sub_f32_e32 v142, v186, v235
	v_sub_f32_e32 v145, v189, v235
	v_sub_f32_e32 v144, v188, v235
	v_pk_mul_f32 v[144:145], v[144:145], v[202:203] op_sel_hi:[1,0]
	v_pk_mul_f32 v[142:143], v[142:143], v[202:203] op_sel_hi:[1,0]
	v_pk_fma_f32 v[144:145], v[76:77], v[144:145], v[80:81]
	v_pk_fma_f32 v[142:143], v[74:75], v[142:143], v[78:79]
	v_pk_fma_f32 v[140:141], v[144:145], s[76:77], v[140:141] op_sel_hi:[1,0,1]
	v_pk_fma_f32 v[138:139], v[142:143], s[76:77], v[138:139] op_sel_hi:[1,0,1]
	global_store_dwordx4 v[190:191], v[138:141], off offset:64
	v_cvt_pk_bf16_f32 v142, v138, v139
	v_cvt_pk_bf16_f32 v143, v140, v141
	global_store_dwordx2 v[200:201], v[142:143], off offset:32
	v_add_f32_e32 v142, v138, v139
	v_mul_f32_e32 v139, v139, v139
	v_fmac_f32_e32 v139, v138, v138
	v_mul_f32_e32 v138, v141, v141
	v_fmac_f32_e32 v138, v140, v140
	v_add_f32_e32 v143, v140, v141
	v_add_f32_e32 v138, v139, v138
	v_add_f32_e32 v142, v142, v143
	v_add_f32_e32 v143, v193, v138
	v_sub_f32_e32 v139, v183, v235
	v_sub_f32_e32 v138, v182, v235
	v_sub_f32_e32 v141, v185, v235
	v_sub_f32_e32 v140, v184, v235
	v_pk_mul_f32 v[140:141], v[140:141], v[202:203] op_sel_hi:[1,0]
	v_pk_mul_f32 v[138:139], v[138:139], v[202:203] op_sel_hi:[1,0]
	v_pk_fma_f32 v[140:141], v[84:85], v[140:141], v[88:89]
	v_pk_fma_f32 v[138:139], v[82:83], v[138:139], v[86:87]
	v_pk_fma_f32 v[136:137], v[140:141], s[76:77], v[136:137] op_sel_hi:[1,0,1]
	v_pk_fma_f32 v[134:135], v[138:139], s[76:77], v[134:135] op_sel_hi:[1,0,1]
	global_store_dwordx4 v[190:191], v[134:137], off offset:512
	v_cvt_pk_bf16_f32 v138, v134, v135
	v_cvt_pk_bf16_f32 v139, v136, v137
	global_store_dwordx2 v[200:201], v[138:139], off offset:256
	v_add_f32_e32 v138, v134, v135
	v_mul_f32_e32 v135, v135, v135
	v_fmac_f32_e32 v135, v134, v134
	v_mul_f32_e32 v134, v137, v137
	v_fmac_f32_e32 v134, v136, v136
	v_add_f32_e32 v139, v136, v137
	v_add_f32_e32 v134, v135, v134
	v_add_f32_e32 v138, v138, v139
	v_add_f32_e32 v139, v134, v143
	v_sub_f32_e32 v135, v179, v235
	v_sub_f32_e32 v134, v178, v235
	v_sub_f32_e32 v137, v181, v235
	v_sub_f32_e32 v136, v180, v235
	v_pk_mul_f32 v[136:137], v[136:137], v[202:203] op_sel_hi:[1,0]
	v_pk_mul_f32 v[134:135], v[134:135], v[202:203] op_sel_hi:[1,0]
	v_pk_fma_f32 v[136:137], v[68:69], v[136:137], v[72:73]
	v_pk_fma_f32 v[134:135], v[66:67], v[134:135], v[70:71]
	v_pk_fma_f32 v[132:133], v[136:137], s[76:77], v[132:133] op_sel_hi:[1,0,1]
	v_pk_fma_f32 v[130:131], v[134:135], s[76:77], v[130:131] op_sel_hi:[1,0,1]
	global_store_dwordx4 v[190:191], v[130:133], off offset:576
	v_cvt_pk_bf16_f32 v134, v130, v131
	v_cvt_pk_bf16_f32 v135, v132, v133
	global_store_dwordx2 v[200:201], v[134:135], off offset:288
	v_add_f32_e32 v134, v130, v131
	v_mul_f32_e32 v131, v131, v131
	v_add_f32_e32 v192, 0, v192
	v_fmac_f32_e32 v131, v130, v130
	v_mul_f32_e32 v130, v133, v133
	v_add_f32_e32 v142, v142, v192
	v_add_f32_e32 v135, v132, v133
	v_fmac_f32_e32 v130, v132, v132
	v_add_f32_e32 v138, v138, v142
	v_add_f32_e32 v134, v134, v135
	v_add_f32_e32 v130, v131, v130
	v_add_f32_e32 v134, v134, v138
	v_add_f32_e32 v132, v130, v139
	v_mov_b32_e32 v130, v134
	v_mov_b32_e32 v133, v132
	s_nop 0
	v_permlane16_swap_b32_e32 v134, v130
	v_permlane16_swap_b32_e32 v132, v133
	v_add_f32_e32 v130, v134, v130
	v_add_f32_e32 v132, v132, v133
	v_mov_b32_e32 v131, v130
	v_mov_b32_e32 v133, v132
	s_nop 0
	v_permlane32_swap_b32_e32 v130, v131
	v_permlane32_swap_b32_e32 v132, v133
	s_and_saveexec_b64 s[2:3], s[6:7]
	s_cbranch_execz .LBB0_981
	v_add_f32_e32 v132, v132, v133
	v_add_f32_e32 v133, v130, v131
	v_lshl_add_u64 v[130:131], v[230:231], 3, s[18:19]
	global_atomic_add_f32 v[130:131], v133, off
	global_atomic_add_f32 v[130:131], v132, off offset:4
.LBB0_981:
	s_or_b64 exec, exec, s[2:3]
	v_add_u32_e32 v178, 0x80, v224
	s_and_b64 vcc, exec, s[10:11]
	v_ashrrev_i32_e32 v179, 31, v178
	s_cbranch_vccnz .LBB0_983
	v_lshl_add_u64 v[130:131], v[178:179], 3, s[20:21]
	global_load_dwordx2 v[182:183], v[130:131], off
	s_branch .LBB0_984
.LBB0_983:
	v_mov_b32_e32 v183, 0x45000000
	v_mov_b32_e32 v182, 0
.LBB0_984:
	v_lshlrev_b64 v[130:131], 13, v[178:179]
	v_lshl_add_u64 v[130:131], s[4:5], 0, v[130:131]
	v_lshl_add_u64 v[130:131], v[222:223], 2, v[130:131]
	global_load_dwordx4 v[142:145], v[130:131], off
	global_load_dwordx4 v[138:141], v[130:131], off offset:64
	global_load_dwordx4 v[134:137], v[130:131], off offset:512
	s_nop 0
	global_load_dwordx4 v[130:133], v[130:131], off offset:576
	s_mov_b32 s2, 0x3a000000
	s_nop 0
	v_mov_b32_e32 v228, v233
	v_mul_f32_e32 v181, s2, v232
	v_cndmask_b32_e64 v229, v181, 0, s[58:59]
	v_mov_b32_e32 v184, s2
	v_mov_b32_e32 v185, v229
	v_pk_mul_f32 v[184:185], v[228:229], v[184:185]
	v_sub_f32_e32 v175, v175, v229
	v_sub_f32_e32 v181, v184, v185
	v_add_f32_e32 v181, 0x3727c5ac, v181
	v_rsq_f32_e32 v181, v181
	v_sub_f32_e32 v174, v174, v229
	v_sub_f32_e32 v177, v177, v229
	v_sub_f32_e32 v176, v176, v229
	v_cndmask_b32_e64 v186, v181, 1.0, s[58:59]
	v_lshlrev_b64 v[184:185], 11, v[226:227]
	v_pk_mul_f32 v[176:177], v[176:177], v[186:187] op_sel_hi:[1,0]
	v_pk_mul_f32 v[174:175], v[174:175], v[186:187] op_sel_hi:[1,0]
	v_lshl_add_u64 v[184:185], v[184:185], 0, v[222:223]
	v_pk_fma_f32 v[174:175], v[90:91], v[174:175], v[94:95]
	v_pk_fma_f32 v[176:177], v[92:93], v[176:177], v[96:97]
	v_pk_fma_f32 v[126:127], v[174:175], s[76:77], v[126:127] op_sel_hi:[1,0,1]
	v_pk_fma_f32 v[128:129], v[176:177], s[76:77], v[128:129] op_sel_hi:[1,0,1]
	v_lshl_add_u64 v[174:175], v[184:185], 2, s[12:13]
	v_cvt_pk_bf16_f32 v176, v126, v127
	v_lshl_add_u64 v[184:185], v[184:185], 1, s[14:15]
	global_store_dwordx4 v[174:175], v[126:129], off
	v_cvt_pk_bf16_f32 v177, v128, v129
	global_store_dwordx2 v[184:185], v[176:177], off
	v_add_f32_e32 v176, v126, v127
	v_mul_f32_e32 v127, v127, v127
	v_fmac_f32_e32 v127, v126, v126
	v_mul_f32_e32 v126, v129, v129
	v_add_f32_e32 v177, v128, v129
	v_fmac_f32_e32 v126, v128, v128
	v_add_f32_e32 v176, v176, v177
	v_add_f32_e32 v177, v127, v126
	v_sub_f32_e32 v127, v171, v229
	v_sub_f32_e32 v126, v170, v229
	v_sub_f32_e32 v129, v173, v229
	v_sub_f32_e32 v128, v172, v229
	v_pk_mul_f32 v[128:129], v[128:129], v[186:187] op_sel_hi:[1,0]
	v_pk_mul_f32 v[126:127], v[126:127], v[186:187] op_sel_hi:[1,0]
	v_pk_fma_f32 v[128:129], v[76:77], v[128:129], v[80:81]
	v_pk_fma_f32 v[126:127], v[74:75], v[126:127], v[78:79]
	v_pk_fma_f32 v[124:125], v[128:129], s[76:77], v[124:125] op_sel_hi:[1,0,1]
	v_pk_fma_f32 v[122:123], v[126:127], s[76:77], v[122:123] op_sel_hi:[1,0,1]
	global_store_dwordx4 v[174:175], v[122:125], off offset:64
	v_cvt_pk_bf16_f32 v126, v122, v123
	v_cvt_pk_bf16_f32 v127, v124, v125
	global_store_dwordx2 v[184:185], v[126:127], off offset:32
	v_add_f32_e32 v126, v122, v123
	v_mul_f32_e32 v123, v123, v123
	v_fmac_f32_e32 v123, v122, v122
	v_mul_f32_e32 v122, v125, v125
	v_fmac_f32_e32 v122, v124, v124
	v_add_f32_e32 v127, v124, v125
	v_add_f32_e32 v122, v123, v122
	v_add_f32_e32 v126, v126, v127
	v_add_f32_e32 v127, v177, v122
	v_sub_f32_e32 v123, v167, v229
	v_sub_f32_e32 v122, v166, v229
	v_sub_f32_e32 v125, v169, v229
	v_sub_f32_e32 v124, v168, v229
	v_pk_mul_f32 v[124:125], v[124:125], v[186:187] op_sel_hi:[1,0]
	v_pk_mul_f32 v[122:123], v[122:123], v[186:187] op_sel_hi:[1,0]
	v_pk_fma_f32 v[124:125], v[84:85], v[124:125], v[88:89]
	v_pk_fma_f32 v[122:123], v[82:83], v[122:123], v[86:87]
	v_pk_fma_f32 v[120:121], v[124:125], s[76:77], v[120:121] op_sel_hi:[1,0,1]
	v_pk_fma_f32 v[118:119], v[122:123], s[76:77], v[118:119] op_sel_hi:[1,0,1]
	global_store_dwordx4 v[174:175], v[118:121], off offset:512
	v_cvt_pk_bf16_f32 v122, v118, v119
	v_cvt_pk_bf16_f32 v123, v120, v121
	global_store_dwordx2 v[184:185], v[122:123], off offset:256
	v_add_f32_e32 v122, v118, v119
	v_mul_f32_e32 v119, v119, v119
	v_fmac_f32_e32 v119, v118, v118
	v_mul_f32_e32 v118, v121, v121
	v_fmac_f32_e32 v118, v120, v120
	v_add_f32_e32 v123, v120, v121
	v_add_f32_e32 v118, v119, v118
	v_add_f32_e32 v122, v122, v123
	v_add_f32_e32 v123, v118, v127
	v_sub_f32_e32 v119, v163, v229
	v_sub_f32_e32 v118, v162, v229
	v_sub_f32_e32 v121, v165, v229
	v_sub_f32_e32 v120, v164, v229
	v_pk_mul_f32 v[120:121], v[120:121], v[186:187] op_sel_hi:[1,0]
	v_pk_mul_f32 v[118:119], v[118:119], v[186:187] op_sel_hi:[1,0]
	v_pk_fma_f32 v[120:121], v[68:69], v[120:121], v[72:73]
	v_pk_fma_f32 v[118:119], v[66:67], v[118:119], v[70:71]
	v_pk_fma_f32 v[116:117], v[120:121], s[76:77], v[116:117] op_sel_hi:[1,0,1]
	v_pk_fma_f32 v[114:115], v[118:119], s[76:77], v[114:115] op_sel_hi:[1,0,1]
	global_store_dwordx4 v[174:175], v[114:117], off offset:576
	v_cvt_pk_bf16_f32 v118, v114, v115
	v_cvt_pk_bf16_f32 v119, v116, v117
	global_store_dwordx2 v[184:185], v[118:119], off offset:288
	v_add_f32_e32 v118, v114, v115
	v_mul_f32_e32 v115, v115, v115
	v_add_f32_e32 v176, 0, v176
	v_fmac_f32_e32 v115, v114, v114
	v_mul_f32_e32 v114, v117, v117
	v_add_f32_e32 v126, v126, v176
	v_add_f32_e32 v119, v116, v117
	v_fmac_f32_e32 v114, v116, v116
	v_add_f32_e32 v122, v122, v126
	v_add_f32_e32 v118, v118, v119
	v_add_f32_e32 v114, v115, v114
	v_add_f32_e32 v118, v118, v122
	v_add_f32_e32 v116, v114, v123
	v_mov_b32_e32 v114, v118
	v_mov_b32_e32 v117, v116
	s_nop 0
	v_permlane16_swap_b32_e32 v118, v114
	v_permlane16_swap_b32_e32 v116, v117
	v_add_f32_e32 v114, v118, v114
	v_add_f32_e32 v116, v116, v117
	v_mov_b32_e32 v115, v114
	v_mov_b32_e32 v117, v116
	s_nop 0
	v_permlane32_swap_b32_e32 v114, v115
	v_permlane32_swap_b32_e32 v116, v117
	s_and_saveexec_b64 s[2:3], s[6:7]
	s_cbranch_execz .LBB0_986
	v_add_f32_e32 v116, v116, v117
	v_add_f32_e32 v117, v114, v115
	v_lshl_add_u64 v[114:115], v[226:227], 3, s[18:19]
	global_atomic_add_f32 v[114:115], v117, off
	global_atomic_add_f32 v[114:115], v116, off offset:4
.LBB0_986:
	s_or_b64 exec, exec, s[2:3]
	v_add_u32_e32 v114, 0x90, v224
	s_and_b64 vcc, exec, s[10:11]
	v_ashrrev_i32_e32 v115, 31, v114
	s_cbranch_vccnz .LBB0_988
	v_lshl_add_u64 v[116:117], v[114:115], 3, s[20:21]
	global_load_dwordx2 v[164:165], v[116:117], off
	s_branch .LBB0_989
.LBB0_988:
	v_mov_b32_e32 v165, 0x45000000
	v_mov_b32_e32 v164, 0
.LBB0_989:
	v_lshlrev_b64 v[114:115], 13, v[114:115]
	v_lshl_add_u64 v[114:115], s[4:5], 0, v[114:115]
	v_lshl_add_u64 v[114:115], v[222:223], 2, v[114:115]
	global_load_dwordx4 v[126:129], v[114:115], off
	global_load_dwordx4 v[122:125], v[114:115], off offset:64
	global_load_dwordx4 v[118:121], v[114:115], off offset:512
	s_nop 0
	global_load_dwordx4 v[114:117], v[114:115], off offset:576
	s_mov_b32 s2, 0x3a000000
	s_nop 0
	s_waitcnt vmcnt(27)
	v_mov_b32_e32 v196, v199
	v_mul_f32_e32 v163, s2, v198
	v_cndmask_b32_e64 v197, v163, 0, s[58:59]
	v_mov_b32_e32 v166, s2
	v_mov_b32_e32 v167, v197
	v_pk_mul_f32 v[166:167], v[196:197], v[166:167]
	s_waitcnt vmcnt(27)
	v_sub_f32_e32 v159, v159, v197
	v_sub_f32_e32 v163, v166, v167
	v_add_f32_e32 v163, 0x3727c5ac, v163
	v_rsq_f32_e32 v163, v163
	v_sub_f32_e32 v158, v158, v197
	v_sub_f32_e32 v161, v161, v197
	v_sub_f32_e32 v160, v160, v197
	v_cndmask_b32_e64 v168, v163, 1.0, s[58:59]
	v_lshlrev_b64 v[166:167], 11, v[194:195]
	v_pk_mul_f32 v[160:161], v[160:161], v[168:169] op_sel_hi:[1,0]
	v_pk_mul_f32 v[158:159], v[158:159], v[168:169] op_sel_hi:[1,0]
	v_lshl_add_u64 v[166:167], v[166:167], 0, v[222:223]
	v_pk_fma_f32 v[158:159], v[90:91], v[158:159], v[94:95]
	v_pk_fma_f32 v[160:161], v[92:93], v[160:161], v[96:97]
	v_pk_fma_f32 v[110:111], v[158:159], s[76:77], v[110:111] op_sel_hi:[1,0,1]
	v_pk_fma_f32 v[112:113], v[160:161], s[76:77], v[112:113] op_sel_hi:[1,0,1]
	v_lshl_add_u64 v[158:159], v[166:167], 2, s[12:13]
	v_cvt_pk_bf16_f32 v160, v110, v111
	v_lshl_add_u64 v[166:167], v[166:167], 1, s[14:15]
	global_store_dwordx4 v[158:159], v[110:113], off
	v_cvt_pk_bf16_f32 v161, v112, v113
	global_store_dwordx2 v[166:167], v[160:161], off
	v_add_f32_e32 v160, v110, v111
	v_mul_f32_e32 v111, v111, v111
	v_fmac_f32_e32 v111, v110, v110
	v_mul_f32_e32 v110, v113, v113
	v_add_f32_e32 v161, v112, v113
	v_fmac_f32_e32 v110, v112, v112
	v_add_f32_e32 v160, v160, v161
	v_add_f32_e32 v161, v111, v110
	s_waitcnt vmcnt(28)
	v_sub_f32_e32 v111, v155, v197
	v_sub_f32_e32 v110, v154, v197
	v_sub_f32_e32 v113, v157, v197
	v_sub_f32_e32 v112, v156, v197
	v_pk_mul_f32 v[112:113], v[112:113], v[168:169] op_sel_hi:[1,0]
	v_pk_mul_f32 v[110:111], v[110:111], v[168:169] op_sel_hi:[1,0]
	v_pk_fma_f32 v[112:113], v[76:77], v[112:113], v[80:81]
	v_pk_fma_f32 v[110:111], v[74:75], v[110:111], v[78:79]
	v_pk_fma_f32 v[108:109], v[112:113], s[76:77], v[108:109] op_sel_hi:[1,0,1]
	v_pk_fma_f32 v[106:107], v[110:111], s[76:77], v[106:107] op_sel_hi:[1,0,1]
	global_store_dwordx4 v[158:159], v[106:109], off offset:64
	v_cvt_pk_bf16_f32 v110, v106, v107
	v_cvt_pk_bf16_f32 v111, v108, v109
	global_store_dwordx2 v[166:167], v[110:111], off offset:32
	v_add_f32_e32 v110, v106, v107
	v_mul_f32_e32 v107, v107, v107
	v_fmac_f32_e32 v107, v106, v106
	v_mul_f32_e32 v106, v109, v109
	v_fmac_f32_e32 v106, v108, v108
	v_add_f32_e32 v111, v108, v109
	v_add_f32_e32 v106, v107, v106
	v_add_f32_e32 v110, v110, v111
	v_add_f32_e32 v111, v161, v106
	s_waitcnt vmcnt(29)
	v_sub_f32_e32 v107, v151, v197
	v_sub_f32_e32 v106, v150, v197
	v_sub_f32_e32 v109, v153, v197
	v_sub_f32_e32 v108, v152, v197
	v_pk_mul_f32 v[108:109], v[108:109], v[168:169] op_sel_hi:[1,0]
	v_pk_mul_f32 v[106:107], v[106:107], v[168:169] op_sel_hi:[1,0]
	v_pk_fma_f32 v[108:109], v[84:85], v[108:109], v[88:89]
	v_pk_fma_f32 v[106:107], v[82:83], v[106:107], v[86:87]
	v_pk_fma_f32 v[104:105], v[108:109], s[76:77], v[104:105] op_sel_hi:[1,0,1]
	v_pk_fma_f32 v[102:103], v[106:107], s[76:77], v[102:103] op_sel_hi:[1,0,1]
	global_store_dwordx4 v[158:159], v[102:105], off offset:512
	v_cvt_pk_bf16_f32 v106, v102, v103
	v_cvt_pk_bf16_f32 v107, v104, v105
	global_store_dwordx2 v[166:167], v[106:107], off offset:256
	v_add_f32_e32 v106, v102, v103
	v_mul_f32_e32 v103, v103, v103
	v_fmac_f32_e32 v103, v102, v102
	v_mul_f32_e32 v102, v105, v105
	v_fmac_f32_e32 v102, v104, v104
	v_add_f32_e32 v107, v104, v105
	v_add_f32_e32 v102, v103, v102
	v_add_f32_e32 v106, v106, v107
	v_add_f32_e32 v107, v102, v111
	s_waitcnt vmcnt(30)
	v_sub_f32_e32 v103, v147, v197
	v_sub_f32_e32 v102, v146, v197
	v_sub_f32_e32 v105, v149, v197
	v_sub_f32_e32 v104, v148, v197
	v_pk_mul_f32 v[104:105], v[104:105], v[168:169] op_sel_hi:[1,0]
	v_pk_mul_f32 v[102:103], v[102:103], v[168:169] op_sel_hi:[1,0]
	v_pk_fma_f32 v[104:105], v[68:69], v[104:105], v[72:73]
	v_pk_fma_f32 v[102:103], v[66:67], v[102:103], v[70:71]
	v_pk_fma_f32 v[100:101], v[104:105], s[76:77], v[100:101] op_sel_hi:[1,0,1]
	v_pk_fma_f32 v[98:99], v[102:103], s[76:77], v[98:99] op_sel_hi:[1,0,1]
	global_store_dwordx4 v[158:159], v[98:101], off offset:576
	v_cvt_pk_bf16_f32 v102, v98, v99
	v_cvt_pk_bf16_f32 v103, v100, v101
	global_store_dwordx2 v[166:167], v[102:103], off offset:288
	v_add_f32_e32 v102, v98, v99
	v_mul_f32_e32 v99, v99, v99
	v_add_f32_e32 v160, 0, v160
	v_fmac_f32_e32 v99, v98, v98
	v_mul_f32_e32 v98, v101, v101
	v_add_f32_e32 v110, v110, v160
	v_add_f32_e32 v103, v100, v101
	v_fmac_f32_e32 v98, v100, v100
	v_add_f32_e32 v106, v106, v110
	v_add_f32_e32 v102, v102, v103
	v_add_f32_e32 v98, v99, v98
	v_add_f32_e32 v102, v102, v106
	v_add_f32_e32 v100, v98, v107
	v_mov_b32_e32 v98, v102
	v_mov_b32_e32 v101, v100
	s_nop 0
	v_permlane16_swap_b32_e32 v102, v98
	v_permlane16_swap_b32_e32 v100, v101
	v_add_f32_e32 v98, v102, v98
	v_add_f32_e32 v100, v100, v101
	v_mov_b32_e32 v99, v98
	v_mov_b32_e32 v101, v100
	s_nop 0
	v_permlane32_swap_b32_e32 v98, v99
	v_permlane32_swap_b32_e32 v100, v101
	s_and_saveexec_b64 s[2:3], s[6:7]
	s_cbranch_execz .LBB0_991
	v_add_f32_e32 v100, v100, v101
	v_add_f32_e32 v101, v98, v99
	v_lshl_add_u64 v[98:99], v[194:195], 3, s[18:19]
	global_atomic_add_f32 v[98:99], v101, off
	global_atomic_add_f32 v[98:99], v100, off offset:4
.LBB0_991:
	s_or_b64 exec, exec, s[2:3]
	v_or_b32_e32 v146, 32, v178
	s_and_b64 vcc, exec, s[10:11]
	v_ashrrev_i32_e32 v147, 31, v146
	s_cbranch_vccnz .LBB0_993
	v_lshl_add_u64 v[98:99], v[146:147], 3, s[20:21]
	global_load_dwordx2 v[150:151], v[98:99], off
	s_branch .LBB0_994
.LBB0_993:
	v_mov_b32_e32 v151, 0x45000000
	v_mov_b32_e32 v150, 0
.LBB0_994:
	v_lshlrev_b64 v[98:99], 13, v[146:147]
	v_lshl_add_u64 v[98:99], s[4:5], 0, v[98:99]
	v_lshl_add_u64 v[98:99], v[222:223], 2, v[98:99]
	global_load_dwordx4 v[110:113], v[98:99], off
	global_load_dwordx4 v[106:109], v[98:99], off offset:64
	global_load_dwordx4 v[102:105], v[98:99], off offset:512
	s_nop 0
	global_load_dwordx4 v[98:101], v[98:99], off offset:576
	s_mov_b32 s2, 0x3a000000
	s_nop 0
	s_waitcnt vmcnt(27)
	v_mov_b32_e32 v180, v183
	v_mul_f32_e32 v149, s2, v182
	v_cndmask_b32_e64 v181, v149, 0, s[58:59]
	v_mov_b32_e32 v152, s2
	v_mov_b32_e32 v153, v181
	v_pk_mul_f32 v[152:153], v[180:181], v[152:153]
	s_waitcnt vmcnt(27)
	v_sub_f32_e32 v143, v143, v181
	v_sub_f32_e32 v149, v152, v153
	v_add_f32_e32 v149, 0x3727c5ac, v149
	v_rsq_f32_e32 v149, v149
	v_sub_f32_e32 v142, v142, v181
	v_sub_f32_e32 v145, v145, v181
	v_sub_f32_e32 v144, v144, v181
	v_cndmask_b32_e64 v154, v149, 1.0, s[58:59]
	v_lshlrev_b64 v[152:153], 11, v[178:179]
	v_pk_mul_f32 v[144:145], v[144:145], v[154:155] op_sel_hi:[1,0]
	v_pk_mul_f32 v[142:143], v[142:143], v[154:155] op_sel_hi:[1,0]
	v_lshl_add_u64 v[152:153], v[152:153], 0, v[222:223]
	v_pk_fma_f32 v[142:143], v[90:91], v[142:143], v[94:95]
	v_pk_fma_f32 v[144:145], v[92:93], v[144:145], v[96:97]
	v_pk_fma_f32 v[62:63], v[142:143], s[76:77], v[62:63] op_sel_hi:[1,0,1]
	v_pk_fma_f32 v[64:65], v[144:145], s[76:77], v[64:65] op_sel_hi:[1,0,1]
	v_lshl_add_u64 v[142:143], v[152:153], 2, s[12:13]
	v_cvt_pk_bf16_f32 v144, v62, v63
	v_lshl_add_u64 v[152:153], v[152:153], 1, s[14:15]
	global_store_dwordx4 v[142:143], v[62:65], off
	v_cvt_pk_bf16_f32 v145, v64, v65
	global_store_dwordx2 v[152:153], v[144:145], off
	v_add_f32_e32 v144, v62, v63
	v_mul_f32_e32 v63, v63, v63
	v_fmac_f32_e32 v63, v62, v62
	v_mul_f32_e32 v62, v65, v65
	v_add_f32_e32 v145, v64, v65
	v_fmac_f32_e32 v62, v64, v64
	v_add_f32_e32 v144, v144, v145
	v_add_f32_e32 v145, v63, v62
	s_waitcnt vmcnt(28)
	v_sub_f32_e32 v63, v139, v181
	v_sub_f32_e32 v62, v138, v181
	v_sub_f32_e32 v65, v141, v181
	v_sub_f32_e32 v64, v140, v181
	v_pk_mul_f32 v[64:65], v[64:65], v[154:155] op_sel_hi:[1,0]
	v_pk_mul_f32 v[62:63], v[62:63], v[154:155] op_sel_hi:[1,0]
	v_pk_fma_f32 v[64:65], v[76:77], v[64:65], v[80:81]
	v_pk_fma_f32 v[62:63], v[74:75], v[62:63], v[78:79]
	v_pk_fma_f32 v[60:61], v[64:65], s[76:77], v[60:61] op_sel_hi:[1,0,1]
	v_pk_fma_f32 v[58:59], v[62:63], s[76:77], v[58:59] op_sel_hi:[1,0,1]
	global_store_dwordx4 v[142:143], v[58:61], off offset:64
	v_cvt_pk_bf16_f32 v62, v58, v59
	v_cvt_pk_bf16_f32 v63, v60, v61
	global_store_dwordx2 v[152:153], v[62:63], off offset:32
	v_add_f32_e32 v62, v58, v59
	v_mul_f32_e32 v59, v59, v59
	v_fmac_f32_e32 v59, v58, v58
	v_mul_f32_e32 v58, v61, v61
	v_fmac_f32_e32 v58, v60, v60
	v_add_f32_e32 v63, v60, v61
	v_add_f32_e32 v58, v59, v58
	v_add_f32_e32 v62, v62, v63
	v_add_f32_e32 v63, v145, v58
	s_waitcnt vmcnt(29)
	v_sub_f32_e32 v59, v135, v181
	v_sub_f32_e32 v58, v134, v181
	v_sub_f32_e32 v61, v137, v181
	v_sub_f32_e32 v60, v136, v181
	v_pk_mul_f32 v[60:61], v[60:61], v[154:155] op_sel_hi:[1,0]
	v_pk_mul_f32 v[58:59], v[58:59], v[154:155] op_sel_hi:[1,0]
	v_pk_fma_f32 v[60:61], v[84:85], v[60:61], v[88:89]
	v_pk_fma_f32 v[58:59], v[82:83], v[58:59], v[86:87]
	v_pk_fma_f32 v[56:57], v[60:61], s[76:77], v[56:57] op_sel_hi:[1,0,1]
	v_pk_fma_f32 v[54:55], v[58:59], s[76:77], v[54:55] op_sel_hi:[1,0,1]
	global_store_dwordx4 v[142:143], v[54:57], off offset:512
	v_cvt_pk_bf16_f32 v58, v54, v55
	v_cvt_pk_bf16_f32 v59, v56, v57
	global_store_dwordx2 v[152:153], v[58:59], off offset:256
	v_add_f32_e32 v58, v54, v55
	v_mul_f32_e32 v55, v55, v55
	v_fmac_f32_e32 v55, v54, v54
	v_mul_f32_e32 v54, v57, v57
	v_fmac_f32_e32 v54, v56, v56
	v_add_f32_e32 v59, v56, v57
	v_add_f32_e32 v54, v55, v54
	v_add_f32_e32 v58, v58, v59
	v_add_f32_e32 v59, v54, v63
	s_waitcnt vmcnt(30)
	v_sub_f32_e32 v55, v131, v181
	v_sub_f32_e32 v54, v130, v181
	v_sub_f32_e32 v57, v133, v181
	v_sub_f32_e32 v56, v132, v181
	v_pk_mul_f32 v[56:57], v[56:57], v[154:155] op_sel_hi:[1,0]
	v_pk_mul_f32 v[54:55], v[54:55], v[154:155] op_sel_hi:[1,0]
	v_pk_fma_f32 v[56:57], v[68:69], v[56:57], v[72:73]
	v_pk_fma_f32 v[54:55], v[66:67], v[54:55], v[70:71]
	v_pk_fma_f32 v[52:53], v[56:57], s[76:77], v[52:53] op_sel_hi:[1,0,1]
	v_pk_fma_f32 v[50:51], v[54:55], s[76:77], v[50:51] op_sel_hi:[1,0,1]
	global_store_dwordx4 v[142:143], v[50:53], off offset:576
	v_cvt_pk_bf16_f32 v54, v50, v51
	v_cvt_pk_bf16_f32 v55, v52, v53
	global_store_dwordx2 v[152:153], v[54:55], off offset:288
	v_add_f32_e32 v54, v50, v51
	v_mul_f32_e32 v51, v51, v51
	v_add_f32_e32 v144, 0, v144
	v_fmac_f32_e32 v51, v50, v50
	v_mul_f32_e32 v50, v53, v53
	v_add_f32_e32 v62, v62, v144
	v_add_f32_e32 v55, v52, v53
	v_fmac_f32_e32 v50, v52, v52
	v_add_f32_e32 v58, v58, v62
	v_add_f32_e32 v54, v54, v55
	v_add_f32_e32 v50, v51, v50
	v_add_f32_e32 v54, v54, v58
	v_add_f32_e32 v52, v50, v59
	v_mov_b32_e32 v50, v54
	v_mov_b32_e32 v53, v52
	s_nop 0
	v_permlane16_swap_b32_e32 v54, v50
	v_permlane16_swap_b32_e32 v52, v53
	v_add_f32_e32 v50, v54, v50
	v_add_f32_e32 v52, v52, v53
	v_mov_b32_e32 v51, v50
	v_mov_b32_e32 v53, v52
	s_nop 0
	v_permlane32_swap_b32_e32 v50, v51
	v_permlane32_swap_b32_e32 v52, v53
	s_and_saveexec_b64 s[2:3], s[6:7]
	s_cbranch_execz .LBB0_996
	v_add_f32_e32 v52, v52, v53
	v_add_f32_e32 v53, v50, v51
	v_lshl_add_u64 v[50:51], v[178:179], 3, s[18:19]
	global_atomic_add_f32 v[50:51], v53, off
	global_atomic_add_f32 v[50:51], v52, off offset:4
.LBB0_996:
	s_or_b64 exec, exec, s[2:3]
	v_or_b32_e32 v130, 48, v178
	s_and_b64 vcc, exec, s[10:11]
	v_ashrrev_i32_e32 v131, 31, v130
	s_cbranch_vccnz .LBB0_998
	v_lshl_add_u64 v[50:51], v[130:131], 3, s[20:21]
	global_load_dwordx2 v[134:135], v[50:51], off
	s_branch .LBB0_999
.LBB0_998:
	v_mov_b32_e32 v135, 0x45000000
	v_mov_b32_e32 v134, 0
.LBB0_999:
	v_lshlrev_b64 v[50:51], 13, v[130:131]
	v_lshl_add_u64 v[50:51], s[4:5], 0, v[50:51]
	v_lshl_add_u64 v[50:51], v[222:223], 2, v[50:51]
	global_load_dwordx4 v[62:65], v[50:51], off
	global_load_dwordx4 v[58:61], v[50:51], off offset:64
	global_load_dwordx4 v[54:57], v[50:51], off offset:512
	s_nop 0
	global_load_dwordx4 v[50:53], v[50:51], off offset:576
	s_mov_b32 s2, 0x3a000000
	v_or_b32_e32 v136, 16, v178
	s_waitcnt vmcnt(27)
	v_mov_b32_e32 v162, v165
	v_mul_f32_e32 v133, s2, v164
	v_cndmask_b32_e64 v163, v133, 0, s[58:59]
	v_mov_b32_e32 v138, s2
	v_mov_b32_e32 v139, v163
	v_pk_mul_f32 v[138:139], v[162:163], v[138:139]
	v_ashrrev_i32_e32 v137, 31, v136
	v_sub_f32_e32 v133, v138, v139
	v_add_f32_e32 v133, 0x3727c5ac, v133
	v_rsq_f32_e32 v133, v133
	s_waitcnt vmcnt(27)
	v_sub_f32_e32 v127, v127, v163
	v_sub_f32_e32 v126, v126, v163
	v_sub_f32_e32 v129, v129, v163
	v_cndmask_b32_e64 v140, v133, 1.0, s[58:59]
	v_sub_f32_e32 v128, v128, v163
	v_lshlrev_b64 v[138:139], 11, v[136:137]
	v_pk_mul_f32 v[128:129], v[128:129], v[140:141] op_sel_hi:[1,0]
	v_pk_mul_f32 v[126:127], v[126:127], v[140:141] op_sel_hi:[1,0]
	v_lshl_add_u64 v[138:139], v[138:139], 0, v[222:223]
	v_pk_fma_f32 v[126:127], v[90:91], v[126:127], v[94:95]
	v_pk_fma_f32 v[128:129], v[92:93], v[128:129], v[96:97]
	v_pk_fma_f32 v[46:47], v[126:127], s[76:77], v[46:47] op_sel_hi:[1,0,1]
	v_pk_fma_f32 v[48:49], v[128:129], s[76:77], v[48:49] op_sel_hi:[1,0,1]
	v_lshl_add_u64 v[126:127], v[138:139], 2, s[12:13]
	v_cvt_pk_bf16_f32 v128, v46, v47
	v_lshl_add_u64 v[138:139], v[138:139], 1, s[14:15]
	global_store_dwordx4 v[126:127], v[46:49], off
	v_cvt_pk_bf16_f32 v129, v48, v49
	global_store_dwordx2 v[138:139], v[128:129], off
	v_add_f32_e32 v128, v46, v47
	v_mul_f32_e32 v47, v47, v47
	v_fmac_f32_e32 v47, v46, v46
	v_mul_f32_e32 v46, v49, v49
	v_add_f32_e32 v129, v48, v49
	v_fmac_f32_e32 v46, v48, v48
	v_add_f32_e32 v128, v128, v129
	v_add_f32_e32 v129, v47, v46
	s_waitcnt vmcnt(28)
	v_sub_f32_e32 v47, v123, v163
	v_sub_f32_e32 v46, v122, v163
	v_sub_f32_e32 v49, v125, v163
	v_sub_f32_e32 v48, v124, v163
	v_pk_mul_f32 v[48:49], v[48:49], v[140:141] op_sel_hi:[1,0]
	v_pk_mul_f32 v[46:47], v[46:47], v[140:141] op_sel_hi:[1,0]
	v_pk_fma_f32 v[48:49], v[76:77], v[48:49], v[80:81]
	v_pk_fma_f32 v[46:47], v[74:75], v[46:47], v[78:79]
	v_pk_fma_f32 v[44:45], v[48:49], s[76:77], v[44:45] op_sel_hi:[1,0,1]
	v_pk_fma_f32 v[42:43], v[46:47], s[76:77], v[42:43] op_sel_hi:[1,0,1]
	global_store_dwordx4 v[126:127], v[42:45], off offset:64
	v_cvt_pk_bf16_f32 v46, v42, v43
	v_cvt_pk_bf16_f32 v47, v44, v45
	global_store_dwordx2 v[138:139], v[46:47], off offset:32
	v_add_f32_e32 v46, v42, v43
	v_mul_f32_e32 v43, v43, v43
	v_fmac_f32_e32 v43, v42, v42
	v_mul_f32_e32 v42, v45, v45
	v_fmac_f32_e32 v42, v44, v44
	v_add_f32_e32 v47, v44, v45
	v_add_f32_e32 v42, v43, v42
	v_add_f32_e32 v46, v46, v47
	v_add_f32_e32 v47, v129, v42
	s_waitcnt vmcnt(29)
	v_sub_f32_e32 v43, v119, v163
	v_sub_f32_e32 v42, v118, v163
	v_sub_f32_e32 v45, v121, v163
	v_sub_f32_e32 v44, v120, v163
	v_pk_mul_f32 v[44:45], v[44:45], v[140:141] op_sel_hi:[1,0]
	v_pk_mul_f32 v[42:43], v[42:43], v[140:141] op_sel_hi:[1,0]
	v_pk_fma_f32 v[44:45], v[84:85], v[44:45], v[88:89]
	v_pk_fma_f32 v[42:43], v[82:83], v[42:43], v[86:87]
	v_pk_fma_f32 v[40:41], v[44:45], s[76:77], v[40:41] op_sel_hi:[1,0,1]
	v_pk_fma_f32 v[38:39], v[42:43], s[76:77], v[38:39] op_sel_hi:[1,0,1]
	global_store_dwordx4 v[126:127], v[38:41], off offset:512
	v_cvt_pk_bf16_f32 v42, v38, v39
	v_cvt_pk_bf16_f32 v43, v40, v41
	global_store_dwordx2 v[138:139], v[42:43], off offset:256
	v_add_f32_e32 v42, v38, v39
	v_mul_f32_e32 v39, v39, v39
	v_fmac_f32_e32 v39, v38, v38
	v_mul_f32_e32 v38, v41, v41
	v_fmac_f32_e32 v38, v40, v40
	v_add_f32_e32 v43, v40, v41
	v_add_f32_e32 v38, v39, v38
	v_add_f32_e32 v42, v42, v43
	v_add_f32_e32 v43, v38, v47
	s_waitcnt vmcnt(30)
	v_sub_f32_e32 v39, v115, v163
	v_sub_f32_e32 v38, v114, v163
	v_sub_f32_e32 v41, v117, v163
	v_sub_f32_e32 v40, v116, v163
	v_pk_mul_f32 v[40:41], v[40:41], v[140:141] op_sel_hi:[1,0]
	v_pk_mul_f32 v[38:39], v[38:39], v[140:141] op_sel_hi:[1,0]
	v_pk_fma_f32 v[40:41], v[68:69], v[40:41], v[72:73]
	v_pk_fma_f32 v[38:39], v[66:67], v[38:39], v[70:71]
	v_pk_fma_f32 v[36:37], v[40:41], s[76:77], v[36:37] op_sel_hi:[1,0,1]
	v_pk_fma_f32 v[34:35], v[38:39], s[76:77], v[34:35] op_sel_hi:[1,0,1]
	global_store_dwordx4 v[126:127], v[34:37], off offset:576
	v_cvt_pk_bf16_f32 v38, v34, v35
	v_cvt_pk_bf16_f32 v39, v36, v37
	global_store_dwordx2 v[138:139], v[38:39], off offset:288
	v_add_f32_e32 v38, v34, v35
	v_mul_f32_e32 v35, v35, v35
	v_add_f32_e32 v128, 0, v128
	v_fmac_f32_e32 v35, v34, v34
	v_mul_f32_e32 v34, v37, v37
	v_add_f32_e32 v46, v46, v128
	v_add_f32_e32 v39, v36, v37
	v_fmac_f32_e32 v34, v36, v36
	v_add_f32_e32 v42, v42, v46
	v_add_f32_e32 v38, v38, v39
	v_add_f32_e32 v34, v35, v34
	v_add_f32_e32 v38, v38, v42
	v_add_f32_e32 v36, v34, v43
	v_mov_b32_e32 v34, v38
	v_mov_b32_e32 v37, v36
	s_nop 0
	v_permlane16_swap_b32_e32 v38, v34
	v_permlane16_swap_b32_e32 v36, v37
	v_add_f32_e32 v34, v38, v34
	v_add_f32_e32 v36, v36, v37
	v_mov_b32_e32 v35, v34
	v_mov_b32_e32 v37, v36
	s_nop 0
	v_permlane32_swap_b32_e32 v34, v35
	v_permlane32_swap_b32_e32 v36, v37
	s_and_saveexec_b64 s[2:3], s[6:7]
	s_cbranch_execz .LBB0_1001
	v_add_f32_e32 v36, v36, v37
	v_add_f32_e32 v37, v34, v35
	v_lshl_add_u64 v[34:35], v[136:137], 3, s[18:19]
	global_atomic_add_f32 v[34:35], v37, off
	global_atomic_add_f32 v[34:35], v36, off offset:4
.LBB0_1001:
	s_or_b64 exec, exec, s[2:3]
	s_mov_b32 s2, 0x3a000000
	s_nop 0
	s_waitcnt vmcnt(23)
	v_mov_b32_e32 v148, v151
	v_mul_f32_e32 v34, s2, v150
	v_cndmask_b32_e64 v149, v34, 0, s[58:59]
	v_mov_b32_e32 v34, s2
	v_mov_b32_e32 v35, v149
	v_pk_mul_f32 v[34:35], v[148:149], v[34:35]
	s_waitcnt vmcnt(23)
	v_sub_f32_e32 v39, v111, v149
	v_sub_f32_e32 v34, v34, v35
	v_add_f32_e32 v34, 0x3727c5ac, v34
	v_rsq_f32_e32 v36, v34
	v_sub_f32_e32 v38, v110, v149
	v_sub_f32_e32 v41, v113, v149
	v_sub_f32_e32 v40, v112, v149
	v_cndmask_b32_e64 v36, v36, 1.0, s[58:59]
	v_lshlrev_b64 v[34:35], 11, v[146:147]
	v_pk_mul_f32 v[40:41], v[40:41], v[36:37] op_sel_hi:[1,0]
	v_pk_mul_f32 v[38:39], v[38:39], v[36:37] op_sel_hi:[1,0]
	v_lshl_add_u64 v[34:35], v[34:35], 0, v[222:223]
	v_pk_fma_f32 v[38:39], v[90:91], v[38:39], v[94:95]
	v_pk_fma_f32 v[40:41], v[92:93], v[40:41], v[96:97]
	v_pk_fma_f32 v[30:31], v[38:39], s[76:77], v[30:31] op_sel_hi:[1,0,1]
	v_pk_fma_f32 v[32:33], v[40:41], s[76:77], v[32:33] op_sel_hi:[1,0,1]
	v_lshl_add_u64 v[38:39], v[34:35], 2, s[12:13]
	global_store_dwordx4 v[38:39], v[30:33], off
	v_cvt_pk_bf16_f32 v40, v30, v31
	v_lshl_add_u64 v[34:35], v[34:35], 1, s[14:15]
	v_add_f32_e32 v37, v30, v31
	v_mul_f32_e32 v31, v31, v31
	v_cvt_pk_bf16_f32 v41, v32, v33
	global_store_dwordx2 v[34:35], v[40:41], off
	v_add_f32_e32 v40, v32, v33
	v_fmac_f32_e32 v31, v30, v30
	v_mul_f32_e32 v30, v33, v33
	v_add_f32_e32 v37, v37, v40
	v_fmac_f32_e32 v30, v32, v32
	v_add_f32_e32 v37, 0, v37
	v_add_f32_e32 v40, v31, v30
	s_waitcnt vmcnt(24)
	v_sub_f32_e32 v31, v107, v149
	v_sub_f32_e32 v30, v106, v149
	v_sub_f32_e32 v33, v109, v149
	v_sub_f32_e32 v32, v108, v149
	v_pk_mul_f32 v[32:33], v[32:33], v[36:37] op_sel_hi:[1,0]
	v_pk_mul_f32 v[30:31], v[30:31], v[36:37] op_sel_hi:[1,0]
	v_pk_fma_f32 v[32:33], v[76:77], v[32:33], v[80:81]
	v_pk_fma_f32 v[30:31], v[74:75], v[30:31], v[78:79]
	v_pk_fma_f32 v[28:29], v[32:33], s[76:77], v[28:29] op_sel_hi:[1,0,1]
	v_pk_fma_f32 v[26:27], v[30:31], s[76:77], v[26:27] op_sel_hi:[1,0,1]
	global_store_dwordx4 v[38:39], v[26:29], off offset:64
	v_cvt_pk_bf16_f32 v30, v26, v27
	v_cvt_pk_bf16_f32 v31, v28, v29
	global_store_dwordx2 v[34:35], v[30:31], off offset:32
	v_add_f32_e32 v30, v26, v27
	v_mul_f32_e32 v27, v27, v27
	v_fmac_f32_e32 v27, v26, v26
	v_mul_f32_e32 v26, v29, v29
	v_fmac_f32_e32 v26, v28, v28
	v_add_f32_e32 v31, v28, v29
	v_add_f32_e32 v26, v27, v26
	v_add_f32_e32 v30, v30, v31
	v_add_f32_e32 v31, v40, v26
	s_waitcnt vmcnt(25)
	v_sub_f32_e32 v27, v103, v149
	v_sub_f32_e32 v26, v102, v149
	v_sub_f32_e32 v29, v105, v149
	v_sub_f32_e32 v28, v104, v149
	v_pk_mul_f32 v[28:29], v[28:29], v[36:37] op_sel_hi:[1,0]
	v_pk_mul_f32 v[26:27], v[26:27], v[36:37] op_sel_hi:[1,0]
	v_pk_fma_f32 v[28:29], v[84:85], v[28:29], v[88:89]
	v_pk_fma_f32 v[26:27], v[82:83], v[26:27], v[86:87]
	v_pk_fma_f32 v[24:25], v[28:29], s[76:77], v[24:25] op_sel_hi:[1,0,1]
	v_pk_fma_f32 v[22:23], v[26:27], s[76:77], v[22:23] op_sel_hi:[1,0,1]
	global_store_dwordx4 v[38:39], v[22:25], off offset:512
	v_cvt_pk_bf16_f32 v26, v22, v23
	v_cvt_pk_bf16_f32 v27, v24, v25
	global_store_dwordx2 v[34:35], v[26:27], off offset:256
	v_add_f32_e32 v26, v22, v23
	v_mul_f32_e32 v23, v23, v23
	v_fmac_f32_e32 v23, v22, v22
	v_mul_f32_e32 v22, v25, v25
	v_fmac_f32_e32 v22, v24, v24
	v_add_f32_e32 v27, v24, v25
	v_add_f32_e32 v22, v23, v22
	v_add_f32_e32 v26, v26, v27
	v_add_f32_e32 v27, v22, v31
	s_waitcnt vmcnt(26)
	v_sub_f32_e32 v23, v99, v149
	v_sub_f32_e32 v22, v98, v149
	v_sub_f32_e32 v25, v101, v149
	v_sub_f32_e32 v24, v100, v149
	v_pk_mul_f32 v[24:25], v[24:25], v[36:37] op_sel_hi:[1,0]
	v_pk_mul_f32 v[22:23], v[22:23], v[36:37] op_sel_hi:[1,0]
	v_pk_fma_f32 v[24:25], v[68:69], v[24:25], v[72:73]
	v_pk_fma_f32 v[22:23], v[66:67], v[22:23], v[70:71]
	v_pk_fma_f32 v[20:21], v[24:25], s[76:77], v[20:21] op_sel_hi:[1,0,1]
	v_pk_fma_f32 v[18:19], v[22:23], s[76:77], v[18:19] op_sel_hi:[1,0,1]
	global_store_dwordx4 v[38:39], v[18:21], off offset:576
	v_cvt_pk_bf16_f32 v22, v18, v19
	v_cvt_pk_bf16_f32 v23, v20, v21
	global_store_dwordx2 v[34:35], v[22:23], off offset:288
	v_add_f32_e32 v22, v18, v19
	v_mul_f32_e32 v19, v19, v19
	v_fmac_f32_e32 v19, v18, v18
	v_mul_f32_e32 v18, v21, v21
	v_add_f32_e32 v30, v30, v37
	v_add_f32_e32 v23, v20, v21
	v_fmac_f32_e32 v18, v20, v20
	v_add_f32_e32 v26, v26, v30
	v_add_f32_e32 v22, v22, v23
	v_add_f32_e32 v18, v19, v18
	v_add_f32_e32 v22, v22, v26
	v_add_f32_e32 v20, v18, v27
	v_mov_b32_e32 v18, v22
	v_mov_b32_e32 v21, v20
	s_nop 0
	v_permlane16_swap_b32_e32 v22, v18
	v_permlane16_swap_b32_e32 v20, v21
	v_add_f32_e32 v18, v22, v18
	v_add_f32_e32 v20, v20, v21
	v_mov_b32_e32 v19, v18
	v_mov_b32_e32 v21, v20
	s_nop 0
	v_permlane32_swap_b32_e32 v18, v19
	v_permlane32_swap_b32_e32 v20, v21
	s_and_saveexec_b64 s[2:3], s[6:7]
	s_cbranch_execz .LBB0_1003
	v_add_f32_e32 v20, v20, v21
	v_add_f32_e32 v21, v18, v19
	v_lshl_add_u64 v[18:19], v[146:147], 3, s[18:19]
	global_atomic_add_f32 v[18:19], v21, off
	global_atomic_add_f32 v[18:19], v20, off offset:4
.LBB0_1003:
	s_or_b64 exec, exec, s[2:3]
	s_mov_b32 s2, 0x3a000000
	s_nop 0
	s_waitcnt vmcnt(19)
	v_mov_b32_e32 v132, v135
	v_mul_f32_e32 v18, s2, v134
	v_cndmask_b32_e64 v133, v18, 0, s[58:59]
	v_mov_b32_e32 v18, s2
	v_mov_b32_e32 v19, v133
	v_pk_mul_f32 v[18:19], v[132:133], v[18:19]
	s_waitcnt vmcnt(19)
	v_sub_f32_e32 v23, v63, v133
	v_sub_f32_e32 v18, v18, v19
	v_add_f32_e32 v18, 0x3727c5ac, v18
	v_rsq_f32_e32 v20, v18
	v_sub_f32_e32 v22, v62, v133
	v_sub_f32_e32 v25, v65, v133
	v_sub_f32_e32 v24, v64, v133
	v_cndmask_b32_e64 v20, v20, 1.0, s[58:59]
	v_lshlrev_b64 v[18:19], 11, v[130:131]
	v_pk_mul_f32 v[24:25], v[24:25], v[20:21] op_sel_hi:[1,0]
	v_pk_mul_f32 v[22:23], v[22:23], v[20:21] op_sel_hi:[1,0]
	v_lshl_add_u64 v[18:19], v[18:19], 0, v[222:223]
	v_pk_fma_f32 v[22:23], v[90:91], v[22:23], v[94:95]
	v_pk_fma_f32 v[24:25], v[92:93], v[24:25], v[96:97]
	v_pk_fma_f32 v[14:15], v[22:23], s[76:77], v[14:15] op_sel_hi:[1,0,1]
	v_pk_fma_f32 v[16:17], v[24:25], s[76:77], v[16:17] op_sel_hi:[1,0,1]
	v_lshl_add_u64 v[22:23], v[18:19], 2, s[12:13]
	global_store_dwordx4 v[22:23], v[14:17], off
	v_cvt_pk_bf16_f32 v24, v14, v15
	v_lshl_add_u64 v[18:19], v[18:19], 1, s[14:15]
	v_add_f32_e32 v21, v14, v15
	v_mul_f32_e32 v15, v15, v15
	v_cvt_pk_bf16_f32 v25, v16, v17
	global_store_dwordx2 v[18:19], v[24:25], off
	v_add_f32_e32 v24, v16, v17
	v_fmac_f32_e32 v15, v14, v14
	v_mul_f32_e32 v14, v17, v17
	v_add_f32_e32 v21, v21, v24
	v_fmac_f32_e32 v14, v16, v16
	v_add_f32_e32 v21, 0, v21
	v_add_f32_e32 v24, v15, v14
	s_waitcnt vmcnt(20)
	v_sub_f32_e32 v15, v59, v133
	v_sub_f32_e32 v14, v58, v133
	v_sub_f32_e32 v17, v61, v133
	v_sub_f32_e32 v16, v60, v133
	v_pk_mul_f32 v[16:17], v[16:17], v[20:21] op_sel_hi:[1,0]
	v_pk_mul_f32 v[14:15], v[14:15], v[20:21] op_sel_hi:[1,0]
	v_pk_fma_f32 v[16:17], v[76:77], v[16:17], v[80:81]
	v_pk_fma_f32 v[14:15], v[74:75], v[14:15], v[78:79]
	v_pk_fma_f32 v[12:13], v[16:17], s[76:77], v[12:13] op_sel_hi:[1,0,1]
	v_pk_fma_f32 v[10:11], v[14:15], s[76:77], v[10:11] op_sel_hi:[1,0,1]
	global_store_dwordx4 v[22:23], v[10:13], off offset:64
	v_cvt_pk_bf16_f32 v14, v10, v11
	v_cvt_pk_bf16_f32 v15, v12, v13
	global_store_dwordx2 v[18:19], v[14:15], off offset:32
	v_add_f32_e32 v14, v10, v11
	v_mul_f32_e32 v11, v11, v11
	v_fmac_f32_e32 v11, v10, v10
	v_mul_f32_e32 v10, v13, v13
	v_fmac_f32_e32 v10, v12, v12
	v_add_f32_e32 v15, v12, v13
	v_add_f32_e32 v10, v11, v10
	v_add_f32_e32 v14, v14, v15
	v_add_f32_e32 v15, v24, v10
	s_waitcnt vmcnt(21)
	v_sub_f32_e32 v11, v55, v133
	v_sub_f32_e32 v10, v54, v133
	v_sub_f32_e32 v13, v57, v133
	v_sub_f32_e32 v12, v56, v133
	v_pk_mul_f32 v[12:13], v[12:13], v[20:21] op_sel_hi:[1,0]
	v_pk_mul_f32 v[10:11], v[10:11], v[20:21] op_sel_hi:[1,0]
	v_pk_fma_f32 v[12:13], v[84:85], v[12:13], v[88:89]
	v_pk_fma_f32 v[10:11], v[82:83], v[10:11], v[86:87]
	v_pk_fma_f32 v[8:9], v[12:13], s[76:77], v[8:9] op_sel_hi:[1,0,1]
	v_pk_fma_f32 v[6:7], v[10:11], s[76:77], v[6:7] op_sel_hi:[1,0,1]
	global_store_dwordx4 v[22:23], v[6:9], off offset:512
	v_cvt_pk_bf16_f32 v10, v6, v7
	v_cvt_pk_bf16_f32 v11, v8, v9
	global_store_dwordx2 v[18:19], v[10:11], off offset:256
	v_add_f32_e32 v10, v6, v7
	v_mul_f32_e32 v7, v7, v7
	v_fmac_f32_e32 v7, v6, v6
	v_mul_f32_e32 v6, v9, v9
	v_fmac_f32_e32 v6, v8, v8
	v_add_f32_e32 v11, v8, v9
	v_add_f32_e32 v6, v7, v6
	v_add_f32_e32 v10, v10, v11
	v_add_f32_e32 v11, v6, v15
	s_waitcnt vmcnt(22)
	v_sub_f32_e32 v7, v51, v133
	v_sub_f32_e32 v6, v50, v133
	v_sub_f32_e32 v9, v53, v133
	v_sub_f32_e32 v8, v52, v133
	v_pk_mul_f32 v[8:9], v[8:9], v[20:21] op_sel_hi:[1,0]
	v_pk_mul_f32 v[6:7], v[6:7], v[20:21] op_sel_hi:[1,0]
	v_pk_fma_f32 v[8:9], v[68:69], v[8:9], v[72:73]
	v_pk_fma_f32 v[6:7], v[66:67], v[6:7], v[70:71]
	v_pk_fma_f32 v[4:5], v[8:9], s[76:77], v[4:5] op_sel_hi:[1,0,1]
	v_pk_fma_f32 v[2:3], v[6:7], s[76:77], v[2:3] op_sel_hi:[1,0,1]
	global_store_dwordx4 v[22:23], v[2:5], off offset:576
	v_cvt_pk_bf16_f32 v6, v2, v3
	v_cvt_pk_bf16_f32 v7, v4, v5
	global_store_dwordx2 v[18:19], v[6:7], off offset:288
	v_add_f32_e32 v6, v2, v3
	v_mul_f32_e32 v3, v3, v3
	v_fmac_f32_e32 v3, v2, v2
	v_mul_f32_e32 v2, v5, v5
	v_add_f32_e32 v14, v14, v21
	v_add_f32_e32 v7, v4, v5
	v_fmac_f32_e32 v2, v4, v4
	v_add_f32_e32 v10, v10, v14
	v_add_f32_e32 v6, v6, v7
	v_add_f32_e32 v2, v3, v2
	v_add_f32_e32 v6, v6, v10
	v_add_f32_e32 v4, v2, v11
	v_mov_b32_e32 v2, v6
	v_mov_b32_e32 v5, v4
	s_nop 0
	v_permlane16_swap_b32_e32 v6, v2
	v_permlane16_swap_b32_e32 v4, v5
	v_add_f32_e32 v2, v6, v2
	v_add_f32_e32 v4, v4, v5
	v_mov_b32_e32 v3, v2
	v_mov_b32_e32 v5, v4
	s_nop 0
	v_permlane32_swap_b32_e32 v2, v3
	v_permlane32_swap_b32_e32 v4, v5
	s_and_saveexec_b64 s[2:3], s[6:7]
	s_cbranch_execz .LBB0_1005
	v_add_f32_e32 v4, v4, v5
	v_add_f32_e32 v5, v2, v3
	v_lshl_add_u64 v[2:3], v[130:131], 3, s[18:19]
	global_atomic_add_f32 v[2:3], v5, off
	global_atomic_add_f32 v[2:3], v4, off offset:4
